# FFN up->down barriers (P2|P3, P11|P12) XCD-local when every workgroup sits on XCC blockIdx%8 (run-time check), else full barrier
# baseline (speedup 1.0000x reference)
; __device__ __forceinline__ int lane_now() { int l; asm volatile("v_mbcnt_lo_u32_b32 %0, -1, 0\n\tv_mbcnt_hi_u32_b32 %0, -1, %0" : "=v"(l)); return l; }
; #define LAS __attribute__((address_space(3)))
; __device__ __forceinline__ unsigned xb_add(unsigned* p, unsigned v) { return __hip_atomic_fetch_add(p, v, __ATOMIC_RELAXED, __HIP_MEMORY_SCOPE_AGENT); }
; __device__ __forceinline__ unsigned xb_xcc_id() { return (unsigned)__builtin_amdgcn_s_getreg((3 << 11) | 20) & 0xFu; }
; __device__ __forceinline__ XcdBarrier xcd_barrier_post(unsigned* bar, volatile LAS unsigned* st, unsigned w0) {
;     XcdBarrier b; b.w0 = w0; b.bar = bar; b.x = xb_xcc_id(); b.st = st;
;     if (w0 && lane_now() == 0) (void)xb_add(&bar[XB_XCNT(b.x)], 1u);
;     return b;
; }
; __global__ void __launch_bounds__(512, 2) mega_fwd(Params p) {
;     ...
;     { const int t0_ = tid; if (t0_ < 2) *(LAS unsigned*)(lds + LDS_BYTES - 64 + 4 * t0_) = 0u; }
;     __syncthreads();
;     const XcdBarrier xbar = xcd_barrier_post((unsigned*)(ws + WS_BAR), (volatile LAS unsigned*)(lds + LDS_BYTES - 64), wave == 0 ? 1u : 0u);
_Z8mega_fwd6Params:
	s_load_dwordx8 s[88:95], s[0:1], 0xe0
	s_load_dwordx8 s[12:19], s[0:1], 0xc0
	v_writelane_b32 v244, s2, 0
	s_load_dword s2, s[0:1], 0x100
	v_and_b32_e32 v1, 0x3ff, v0
	s_add_u32 s6, s0, 0xf8
	s_addc_u32 s7, s1, 0
	v_mbcnt_lo_u32_b32 v2, -1, 0
	v_mbcnt_hi_u32_b32 v2, -1, v2
	s_waitcnt lgkmcnt(0)
	v_writelane_b32 v244, s2, 1
	v_readfirstlane_b32 s2, v1
	s_and_b32 s86, s2, 0xffffffc0
	v_add_u32_e32 v2, s86, v2
	v_cmp_gt_i32_e32 vcc, 2, v2
	v_writelane_b32 v244, s2, 2
	s_and_saveexec_b64 s[2:3], vcc
	v_lshl_add_u32 v2, v2, 2, 0
	v_add_u32_e32 v2, 0x23fc0, v2
	v_mov_b32_e32 v3, 0
	ds_write_b32 v2, v3
	s_or_b64 exec, exec, s[2:3]
	s_add_u32 s2, s92, 0xc0000
	s_addc_u32 s3, s93, 0
	v_writelane_b32 v244, s2, 3
	s_waitcnt lgkmcnt(0)
	s_barrier
	v_writelane_b32 v244, s3, 4
	s_nop 0
	v_readlane_b32 s4, v244, 2
	s_cmp_lt_u32 s4, 64
	s_getreg_b32 s87, hwreg(HW_REG_XCC_ID, 0, 4)
	s_cselect_b64 s[2:3], -1, 0
	s_and_b32 s5, s87, 15
	s_cmp_gt_u32 s4, 63
	v_writelane_b32 v244, s5, 5
	s_cbranch_scc1 .LBB0_7
	v_mbcnt_lo_u32_b32 v2, -1, 0
	v_mbcnt_hi_u32_b32 v2, -1, v2
	s_nop 0
	v_cmp_eq_u32_e32 vcc, 0, v2
	s_and_saveexec_b64 s[4:5], vcc
	s_cbranch_execz .LBB0_6
	s_mov_b64 s[8:9], exec
	v_mbcnt_lo_u32_b32 v2, s8, 0
	v_mbcnt_hi_u32_b32 v2, s9, v2
	v_cmp_eq_u32_e32 vcc, 0, v2
	s_and_b64 s[10:11], exec, vcc
	s_mov_b64 exec, s[10:11]
	s_cbranch_execz .LBB0_6
	v_readlane_b32 s10, v244, 5
	s_bcnt1_i32_b64 s8, s[8:9]
	s_lshl_b32 s10, s10, 8
	v_mov_b32_e32 v3, s8
	v_readlane_b32 s8, v244, 3
	v_mov_b32_e32 v2, s10
	v_readlane_b32 s9, v244, 4
	s_nop 4
	global_atomic_add v2, v3, s[8:9] offset:1024
	v_readlane_b32 s10, v244, 0
	s_and_b32 s10, s10, 7
	v_readlane_b32 s11, v244, 5
	s_cmp_lg_u32 s10, s11
	s_cbranch_scc0 .Lxl_mapok
	v_mov_b32_e32 v2, 0x3e80
	v_mov_b32_e32 v3, 1
	global_atomic_add v2, v3, s[8:9]
.Lxl_mapok:
.LBB0_6:
	s_or_b64 exec, exec, s[4:5]

; #define LAS __attribute__((address_space(3)))
; #define BAR_LDS() do { asm volatile("s_waitcnt lgkmcnt(0)" ::: "memory"); __builtin_amdgcn_s_barrier(); asm volatile("" ::: "memory"); } while (0)
; #define lane (lane_now())
; __device__ __forceinline__ void norm_phase(const float* src, const float* g, const float* mod, int ish, int isc, bf16_t* dst, LAS unsigned char* lds, int gw, int ngw, int wave, int lane) {
;     LAS float* GSl = (LAS float*)lds; LAS float* SHl = GSl + 4096;
;     for (int i = wave * 64 + lane; i < 4096; i += 512) { const int b = i >> 10, c = i & 1023; GSl[i] = g[c] * (1.f + mod[(size_t)b * NMOD + isc * 1024 + c]); SHl[i] = mod[(size_t)b * NMOD + ish * 1024 + c]; }
;     BAR_LDS();
; __global__ void __launch_bounds__(512, 2) mega_fwd(Params p) {
;     ...
;     grid.sync();
;     norm_phase(p.x, p.norm1_g, mod, 0, 1, XN, lds, gw, ngw, wave, lane);
;     xcd_barrier(xbar);
.Lgb0_141:
	s_mov_b64 exec, -1
	v_readlane_b32 s0, v245, 0
	v_readlane_b32 s1, v245, 1
	v_readlane_b32 s2, v245, 2
	v_readlane_b32 s3, v245, 3
	v_readlane_b32 s4, v245, 4
	v_readlane_b32 s5, v245, 5
	v_readlane_b32 s6, v245, 6
	v_readlane_b32 s7, v245, 7
	v_readlane_b32 s8, v245, 8
	v_readlane_b32 s9, v245, 9
	v_readlane_b32 s10, v245, 10
	v_readlane_b32 s11, v245, 11
	v_readlane_b32 s12, v245, 12
	v_readlane_b32 s13, v245, 13
	v_readlane_b32 s14, v245, 14
	v_readlane_b32 s15, v245, 15
	v_readlane_b32 s16, v245, 16
	v_readlane_b32 s17, v245, 17
	v_readlane_b32 s18, v245, 18
	v_readlane_b32 s19, v245, 19
	v_readlane_b32 s20, v245, 20
	v_readlane_b32 s21, v245, 21
	v_readlane_b32 s22, v245, 22
	v_readlane_b32 s23, v245, 23
	v_readlane_b32 s24, v245, 24
	v_readlane_b32 s25, v245, 25
	v_readlane_b32 s26, v245, 26
	v_readlane_b32 s27, v245, 27
	v_readlane_b32 s28, v245, 28
	v_readlane_b32 s29, v245, 29
	v_readlane_b32 s30, v245, 30
	v_readlane_b32 s31, v245, 31
	v_readlane_b32 s32, v245, 32
	v_readlane_b32 s33, v245, 33
	v_readlane_b32 s34, v245, 34
	v_readlane_b32 s35, v245, 35
	v_readlane_b32 s36, v245, 36
	v_readlane_b32 s37, v245, 37
	v_readlane_b32 s38, v245, 38
	v_readlane_b32 s39, v245, 39
	v_readlane_b32 s40, v245, 40
	v_readlane_b32 s41, v245, 41
	v_readlane_b32 s42, v245, 42
	v_readlane_b32 s43, v245, 43
	v_readlane_b32 s44, v245, 44
	v_readlane_b32 s45, v245, 45
	v_readlane_b32 s46, v245, 46
	v_readlane_b32 s47, v245, 47
	v_readlane_b32 s48, v245, 48
	v_readlane_b32 s49, v245, 49
	v_readlane_b32 s50, v245, 50
	v_readlane_b32 s51, v245, 51
	v_readlane_b32 s52, v245, 52
	v_readlane_b32 s53, v245, 53
	v_readlane_b32 s54, v245, 54
	v_readlane_b32 s55, v245, 55
	v_readlane_b32 s56, v245, 56
	v_readlane_b32 s57, v245, 57
	v_readlane_b32 s58, v245, 58
	v_readlane_b32 s59, v245, 59
	v_readlane_b32 s60, v245, 60
	v_readlane_b32 s61, v245, 61
	v_readlane_b32 s62, v245, 62
	v_readlane_b32 s63, v245, 63
	v_readlane_b32 s64, v246, 0
	v_readlane_b32 s65, v246, 1
	v_readlane_b32 s66, v246, 2
	v_readlane_b32 s67, v246, 3
	v_readlane_b32 s68, v246, 4
	v_readlane_b32 s69, v246, 5
	v_readlane_b32 s70, v246, 6
	v_readlane_b32 s71, v246, 7
	v_readlane_b32 s72, v246, 8
	v_readlane_b32 s73, v246, 9
	v_readlane_b32 s74, v246, 10
	v_readlane_b32 s75, v246, 11
	v_readlane_b32 s76, v246, 12
	v_readlane_b32 s77, v246, 13
	v_readlane_b32 s78, v246, 14
	v_readlane_b32 s79, v246, 15
	v_readlane_b32 s80, v246, 16
	v_readlane_b32 s81, v246, 17
	v_readlane_b32 s82, v246, 18
	v_readlane_b32 s83, v246, 19
	v_readlane_b32 s84, v246, 20
	v_readlane_b32 s85, v246, 21
	v_readlane_b32 s86, v246, 22
	v_readlane_b32 s87, v246, 23
	v_readlane_b32 s88, v246, 24
	v_readlane_b32 s89, v246, 25
	v_readlane_b32 s90, v246, 26
	v_readlane_b32 s91, v246, 27
	v_readlane_b32 s92, v246, 28
	v_readlane_b32 s93, v246, 29
	v_readlane_b32 s94, v246, 30
	v_readlane_b32 s95, v246, 31
	v_readlane_b32 s96, v246, 32
	v_readlane_b32 s97, v246, 33
	v_readlane_b32 vcc_lo, v246, 34
	v_readlane_b32 vcc_hi, v246, 35
	s_nop 7
	s_barrier
	v_mov_b32_e32 v245, 0xc3e80
	global_load_dword v245, v245, s[92:93] sc1
	s_waitcnt vmcnt(0)
	v_readfirstlane_b32 s100, v245
	s_cmp_eq_u32 s100, 0
	s_cselect_b32 s100, 1, 0
	s_cmp_eq_u32 s94, 0x100
	s_cselect_b32 s100, s100, 0
	v_writelane_b32 v244, s100, 61
	v_mbcnt_lo_u32_b32 v0, -1, 0
	v_mbcnt_hi_u32_b32 v0, -1, v0
	s_movk_i32 s0, 0x1000
	v_add_u32_e32 v2, s86, v0
	v_cmp_gt_i32_e32 vcc, s0, v2
	s_and_saveexec_b64 s[6:7], vcc
	s_cbranch_execz .LBB0_84
	v_max_i32_e32 v1, 0xe00, v2
	v_sub_u32_e32 v1, v1, v2
	v_add_u32_e32 v3, 0x1ff, v1
	s_movk_i32 s0, 0xa00
	v_cmp_gt_u32_e64 s[10:11], s0, v3
	s_movk_i32 s0, 0x9ff
	v_cmp_lt_u32_e32 vcc, s0, v3
	s_and_saveexec_b64 s[16:17], vcc
	s_cbranch_execz .LBB0_81
	v_readlane_b32 s0, v244, 2
	v_lshrrev_b32_e32 v1, 9, v3
	s_and_b32 s0, s0, 0x3c0
	v_add_u16_e32 v4, s0, v0
	v_and_b32_e32 v5, 0x3ff, v1
	v_lshlrev_b16_e32 v6, 9, v1
	s_mov_b32 s4, 0x80000
	v_and_b32_e32 v4, 0x3ff, v4
	v_and_b32_e32 v6, 0x200, v6
	v_cmp_gt_u16_e32 vcc, 2, v5
	v_cmp_gt_u32_e64 s[4:5], s4, v3
	v_cmp_le_u16_e64 s[0:1], v6, v4
	s_and_b64 s[4:5], vcc, s[4:5]
	s_and_b64 s[20:21], s[4:5], s[0:1]
	s_mov_b64 s[4:5], -1
	s_and_saveexec_b64 s[0:1], s[20:21]
	s_cbranch_execz .LBB0_80
	v_add_u32_e32 v3, 0x200, v2
	v_add_u32_e32 v8, -1, v1
	v_cmp_lt_u32_e32 vcc, 1, v8
	v_mov_b32_e32 v6, 0
	v_mov_b64_e32 v[4:5], v[2:3]
	s_and_saveexec_b64 s[4:5], vcc
	s_cbranch_execz .LBB0_77
	v_lshrrev_b32_e32 v4, 1, v8
	s_lshl_b32 s20, s83, 8
	v_add_u32_e32 v4, 1, v4
	s_add_i32 s20, s20, 0
	v_and_b32_e32 v9, -2, v4
	s_mov_b32 s22, 0
	v_lshl_add_u32 v10, v0, 2, s20
	s_mov_b64 s[20:21], 0
	v_mov_b32_e32 v7, 0
	s_movk_i32 s23, 0x1000
	v_mov_b64_e32 v[4:5], v[2:3]

; __device__ __forceinline__ int lane_now() { int l; asm volatile("v_mbcnt_lo_u32_b32 %0, -1, 0\n\tv_mbcnt_hi_u32_b32 %0, -1, %0" : "=v"(l)); return l; }
; __device__ __forceinline__ unsigned xb_ld(unsigned* p)              { return __hip_atomic_load(p, __ATOMIC_RELAXED, __HIP_MEMORY_SCOPE_AGENT); }
; __device__ __forceinline__ unsigned xb_add(unsigned* p, unsigned v) { return __hip_atomic_fetch_add(p, v, __ATOMIC_RELAXED, __HIP_MEMORY_SCOPE_AGENT); }
; #define XB_SPIN(cond, bar) do { unsigned _sp = 0; while (cond) { __builtin_amdgcn_s_sleep(1); \
;     if ((++_sp & 255u) == 0u) { if (xb_ld(&(bar)[XB_TMO])) break; if (_sp > XB_SPIN_CAP) { atomicAdd(&(bar)[XB_TMO], 1u); break; } } } } while (0)
; __device__ __forceinline__ void xcd_barrier(const XcdBarrier& b) {
;     asm volatile("s_waitcnt vmcnt(0)" ::: "memory");
;     __syncthreads();
;     if (b.w0 && lane_now() == 0) {
;         unsigned* bar = b.bar;
;         __builtin_amdgcn_s_waitcnt(0);
;         unsigned nloc = b.st[0], nx = b.st[1];
;         if (nloc == 0u) { xcd_barrier_complete(bar, b.x, nloc, nx); b.st[0] = nloc; b.st[1] = nx; }
;         const unsigned old = xb_add(&bar[XB_XSUB(b.x)], 1u);
;         const unsigned gen = old / nloc;
;         if (old + 1u == (gen + 1u) * nloc) {
;             __builtin_amdgcn_fence(__ATOMIC_RELEASE, "agent");
;             asm volatile("s_waitcnt vmcnt(0)" ::: "memory");
;             const unsigned og = xb_add(&bar[XB_TOP], 1u);
;             const unsigned tg = og / nx;
;             if (og + 1u == (tg + 1u) * nx) xb_add(&bar[XB_TOPGEN], 1u);
;             else XB_SPIN(xb_ld(&bar[XB_TOPGEN]) == tg, bar);
;             __builtin_amdgcn_fence(__ATOMIC_ACQUIRE, "agent");
;             xb_add(&bar[XB_XGEN(b.x)], 1u);
.LBB0_190:
	s_andn2_saveexec_b64 s[10:11], s[10:11]
	s_cbranch_execz .LBB0_210
	s_mov_b64 s[10:11], exec
	v_readlane_b32 s100, v244, 61
	s_cmp_lg_u32 s100, 0
	s_cbranch_scc1 .LBB0_207
	buffer_wbl2 sc1
	s_waitcnt lgkmcnt(0)
	s_waitcnt vmcnt(0)
	v_mbcnt_lo_u32_b32 v1, s10, 0
	v_mbcnt_hi_u32_b32 v1, s11, v1
	v_cmp_eq_u32_e32 vcc, 0, v1
	s_and_saveexec_b64 s[16:17], vcc
	s_cbranch_execz .LBB0_193
	s_bcnt1_i32_b64 s10, s[10:11]
	v_mov_b32_e32 v2, 0xc3000
	v_mov_b32_e32 v3, s10
	global_atomic_add v2, v2, v3, s[92:93] offset:1024 sc0

; __device__ __forceinline__ int lane_now() { int l; asm volatile("v_mbcnt_lo_u32_b32 %0, -1, 0\n\tv_mbcnt_hi_u32_b32 %0, -1, %0" : "=v"(l)); return l; }
; __device__ __forceinline__ unsigned xb_ld(unsigned* p)              { return __hip_atomic_load(p, __ATOMIC_RELAXED, __HIP_MEMORY_SCOPE_AGENT); }
; __device__ __forceinline__ unsigned xb_add(unsigned* p, unsigned v) { return __hip_atomic_fetch_add(p, v, __ATOMIC_RELAXED, __HIP_MEMORY_SCOPE_AGENT); }
; #define XB_SPIN(cond, bar) do { unsigned _sp = 0; while (cond) { __builtin_amdgcn_s_sleep(1); \
;     if ((++_sp & 255u) == 0u) { if (xb_ld(&(bar)[XB_TMO])) break; if (_sp > XB_SPIN_CAP) { atomicAdd(&(bar)[XB_TMO], 1u); break; } } } } while (0)
; __device__ __forceinline__ void xcd_barrier(const XcdBarrier& b) {
;     asm volatile("s_waitcnt vmcnt(0)" ::: "memory");
;     __syncthreads();
;     if (b.w0 && lane_now() == 0) {
;         unsigned* bar = b.bar;
;         __builtin_amdgcn_s_waitcnt(0);
;         unsigned nloc = b.st[0], nx = b.st[1];
;         if (nloc == 0u) { xcd_barrier_complete(bar, b.x, nloc, nx); b.st[0] = nloc; b.st[1] = nx; }
;         const unsigned old = xb_add(&bar[XB_XSUB(b.x)], 1u);
;         const unsigned gen = old / nloc;
;         if (old + 1u == (gen + 1u) * nloc) {
;             __builtin_amdgcn_fence(__ATOMIC_RELEASE, "agent");
;             asm volatile("s_waitcnt vmcnt(0)" ::: "memory");
;             const unsigned og = xb_add(&bar[XB_TOP], 1u);
;             const unsigned tg = og / nx;
;             if (og + 1u == (tg + 1u) * nx) xb_add(&bar[XB_TOPGEN], 1u);
;             else XB_SPIN(xb_ld(&bar[XB_TOPGEN]) == tg, bar);
;             __builtin_amdgcn_fence(__ATOMIC_ACQUIRE, "agent");
;             xb_add(&bar[XB_XGEN(b.x)], 1u);
.LBB0_1351:
	s_andn2_saveexec_b64 s[6:7], s[6:7]
	s_cbranch_execz .LBB0_1371
	s_mov_b64 s[6:7], exec
	v_readlane_b32 s100, v244, 61
	s_cmp_lg_u32 s100, 0
	s_cbranch_scc1 .LBB0_1368
	buffer_wbl2 sc1
	s_waitcnt lgkmcnt(0)
	s_waitcnt vmcnt(0)
	v_mbcnt_lo_u32_b32 v1, s6, 0
	v_mbcnt_hi_u32_b32 v1, s7, v1
	v_cmp_eq_u32_e32 vcc, 0, v1
	s_and_saveexec_b64 s[8:9], vcc
	s_cbranch_execz .LBB0_1354
	s_bcnt1_i32_b64 s6, s[6:7]
	v_mov_b32_e32 v2, 0xc3000
	v_mov_b32_e32 v3, s6
	global_atomic_add v2, v2, v3, s[92:93] offset:1024 sc0
